# sample-row ln2 fused into the phase-11 tail (16-workgroup statistics rendezvous, one polling wave per workgroup, no L2 invalidate); last grid barrier + phase 12 removed
# speedup vs baseline: 1.0079x; 1.0079x over previous
.LBB0_1340:
	v_or_b32_e32 v0, s20, v55
	v_mad_i64_i32 v[48:49], s[20:21], v0, s14, v[34:35]
	v_or_b32_e32 v0, s19, v55
	v_mul_u32_u24_e32 v4, 0xb00, v0
	global_load_dwordx4 v[0:3], v[48:49], off
	v_lshlrev_b32_e32 v4, 1, v4
	v_mov_b32_e32 v5, v33
	v_lshl_add_u64 v[104:105], v[36:37], 0, v[4:5]
	global_load_dwordx4 v[4:7], v[104:105], off
	v_add_co_u32_e32 v106, vcc, s15, v104
	v_ashrrev_i32_e32 v45, 31, v44
	s_nop 0
	v_addc_co_u32_e32 v107, vcc, 0, v105, vcc
	global_load_dwordx4 v[8:11], v[106:107], off
	global_load_dwordx4 v[72:75], v[48:49], off offset:32
	global_load_dwordx4 v[76:79], v[104:105], off offset:32
	global_load_dwordx4 v[80:83], v[48:49], off offset:672
	global_load_dwordx4 v[84:87], v[106:107], off offset:32
	global_load_dwordx4 v[88:91], v[48:49], off offset:64
	global_load_dwordx4 v[92:95], v[104:105], off offset:672
	global_load_dwordx4 v[96:99], v[104:105], off offset:64
	s_add_i32 s18, s18, s92
	s_add_i32 s8, s8, s9
	s_add_i32 s10, s10, s11
	s_cmpk_lt_i32 s18, 0x100
	s_waitcnt vmcnt(8)
	v_mfma_f32_32x32x16_bf16 v[16:31], v[0:3], v[4:7], 0
	s_waitcnt vmcnt(7)
	v_mfma_f32_32x32x16_bf16 v[0:15], v[0:3], v[8:11], 0
	s_waitcnt vmcnt(5)
	v_mfma_f32_32x32x16_bf16 v[16:31], v[72:75], v[76:79], v[16:31]
	global_load_dwordx4 v[76:79], v[106:107], off offset:64
	global_load_dwordx4 v[100:103], v[48:49], off offset:96
	s_waitcnt vmcnt(5)
	v_mfma_f32_32x32x16_bf16 v[0:15], v[72:75], v[84:87], v[0:15]
	global_load_dwordx4 v[72:75], v[104:105], off offset:96
	s_waitcnt vmcnt(3)
	v_mfma_f32_32x32x16_bf16 v[16:31], v[88:91], v[96:99], v[16:31]
	global_load_dwordx4 v[84:87], v[106:107], off offset:96
	global_load_dwordx4 v[96:99], v[48:49], off offset:128
	s_waitcnt vmcnt(4)
	v_mfma_f32_32x32x16_bf16 v[0:15], v[88:91], v[76:79], v[0:15]
	global_load_dwordx4 v[76:79], v[104:105], off offset:128
	s_waitcnt vmcnt(3)
	v_mfma_f32_32x32x16_bf16 v[16:31], v[100:103], v[72:75], v[16:31]
	global_load_dwordx4 v[72:75], v[106:107], off offset:128
	global_load_dwordx4 v[88:91], v[48:49], off offset:160
	s_waitcnt vmcnt(4)
	v_mfma_f32_32x32x16_bf16 v[0:15], v[100:103], v[84:87], v[0:15]
	global_load_dwordx4 v[84:87], v[104:105], off offset:160
	s_waitcnt vmcnt(3)
	v_mfma_f32_32x32x16_bf16 v[16:31], v[96:99], v[76:79], v[16:31]
	global_load_dwordx4 v[76:79], v[106:107], off offset:160
	global_load_dwordx4 v[100:103], v[48:49], off offset:192
	s_waitcnt vmcnt(4)
	v_mfma_f32_32x32x16_bf16 v[0:15], v[96:99], v[72:75], v[0:15]
	global_load_dwordx4 v[72:75], v[104:105], off offset:192
	s_waitcnt vmcnt(3)
	v_mfma_f32_32x32x16_bf16 v[16:31], v[88:91], v[84:87], v[16:31]
	global_load_dwordx4 v[84:87], v[106:107], off offset:192
	global_load_dwordx4 v[96:99], v[48:49], off offset:224
	s_waitcnt vmcnt(4)
	v_mfma_f32_32x32x16_bf16 v[0:15], v[88:91], v[76:79], v[0:15]
	global_load_dwordx4 v[76:79], v[104:105], off offset:224
	s_waitcnt vmcnt(3)
	v_mfma_f32_32x32x16_bf16 v[16:31], v[100:103], v[72:75], v[16:31]
	global_load_dwordx4 v[72:75], v[106:107], off offset:224
	global_load_dwordx4 v[88:91], v[48:49], off offset:256
	s_waitcnt vmcnt(4)
	v_mfma_f32_32x32x16_bf16 v[0:15], v[100:103], v[84:87], v[0:15]
	global_load_dwordx4 v[84:87], v[104:105], off offset:256
	s_waitcnt vmcnt(3)
	v_mfma_f32_32x32x16_bf16 v[16:31], v[96:99], v[76:79], v[16:31]
	global_load_dwordx4 v[76:79], v[106:107], off offset:256
	global_load_dwordx4 v[100:103], v[48:49], off offset:288
	s_waitcnt vmcnt(4)
	v_mfma_f32_32x32x16_bf16 v[0:15], v[96:99], v[72:75], v[0:15]
	global_load_dwordx4 v[72:75], v[104:105], off offset:288
	s_waitcnt vmcnt(3)
	v_mfma_f32_32x32x16_bf16 v[16:31], v[88:91], v[84:87], v[16:31]
	global_load_dwordx4 v[84:87], v[106:107], off offset:288
	global_load_dwordx4 v[96:99], v[48:49], off offset:320
	s_waitcnt vmcnt(4)
	v_mfma_f32_32x32x16_bf16 v[0:15], v[88:91], v[76:79], v[0:15]
	global_load_dwordx4 v[76:79], v[104:105], off offset:320
	s_waitcnt vmcnt(3)
	v_mfma_f32_32x32x16_bf16 v[16:31], v[100:103], v[72:75], v[16:31]
	global_load_dwordx4 v[72:75], v[106:107], off offset:320
	global_load_dwordx4 v[88:91], v[48:49], off offset:352
	s_waitcnt vmcnt(4)
	v_mfma_f32_32x32x16_bf16 v[0:15], v[100:103], v[84:87], v[0:15]
	global_load_dwordx4 v[84:87], v[104:105], off offset:352
	s_waitcnt vmcnt(3)
	v_mfma_f32_32x32x16_bf16 v[16:31], v[96:99], v[76:79], v[16:31]
	global_load_dwordx4 v[76:79], v[106:107], off offset:352
	global_load_dwordx4 v[100:103], v[48:49], off offset:384
	s_waitcnt vmcnt(4)
	v_mfma_f32_32x32x16_bf16 v[0:15], v[96:99], v[72:75], v[0:15]
	global_load_dwordx4 v[72:75], v[104:105], off offset:384
	s_waitcnt vmcnt(3)
	v_mfma_f32_32x32x16_bf16 v[16:31], v[88:91], v[84:87], v[16:31]
	global_load_dwordx4 v[84:87], v[106:107], off offset:384
	global_load_dwordx4 v[96:99], v[48:49], off offset:416
	s_waitcnt vmcnt(4)
	v_mfma_f32_32x32x16_bf16 v[0:15], v[88:91], v[76:79], v[0:15]
	global_load_dwordx4 v[76:79], v[104:105], off offset:416
	s_waitcnt vmcnt(3)
	v_mfma_f32_32x32x16_bf16 v[16:31], v[100:103], v[72:75], v[16:31]
	global_load_dwordx4 v[72:75], v[106:107], off offset:416
	global_load_dwordx4 v[88:91], v[48:49], off offset:448
	s_waitcnt vmcnt(4)
	v_mfma_f32_32x32x16_bf16 v[0:15], v[100:103], v[84:87], v[0:15]
	global_load_dwordx4 v[84:87], v[104:105], off offset:448
	s_waitcnt vmcnt(3)
	v_mfma_f32_32x32x16_bf16 v[16:31], v[96:99], v[76:79], v[16:31]
	global_load_dwordx4 v[76:79], v[106:107], off offset:448
	global_load_dwordx4 v[100:103], v[48:49], off offset:480
	s_waitcnt vmcnt(4)
	v_mfma_f32_32x32x16_bf16 v[0:15], v[96:99], v[72:75], v[0:15]
	global_load_dwordx4 v[72:75], v[104:105], off offset:480
	s_waitcnt vmcnt(3)
	v_mfma_f32_32x32x16_bf16 v[16:31], v[88:91], v[84:87], v[16:31]
	global_load_dwordx4 v[84:87], v[106:107], off offset:480
	global_load_dwordx4 v[96:99], v[48:49], off offset:512
	s_waitcnt vmcnt(4)
	v_mfma_f32_32x32x16_bf16 v[0:15], v[88:91], v[76:79], v[0:15]
	global_load_dwordx4 v[76:79], v[104:105], off offset:512
	s_waitcnt vmcnt(3)
	v_mfma_f32_32x32x16_bf16 v[16:31], v[100:103], v[72:75], v[16:31]
	global_load_dwordx4 v[72:75], v[106:107], off offset:512
	global_load_dwordx4 v[88:91], v[48:49], off offset:544
	s_waitcnt vmcnt(4)
	v_mfma_f32_32x32x16_bf16 v[0:15], v[100:103], v[84:87], v[0:15]
	global_load_dwordx4 v[84:87], v[104:105], off offset:544
	s_waitcnt vmcnt(3)
	v_mfma_f32_32x32x16_bf16 v[16:31], v[96:99], v[76:79], v[16:31]
	global_load_dwordx4 v[76:79], v[106:107], off offset:544
	global_load_dwordx4 v[100:103], v[48:49], off offset:576
	s_waitcnt vmcnt(4)
	v_mfma_f32_32x32x16_bf16 v[0:15], v[96:99], v[72:75], v[0:15]
	global_load_dwordx4 v[72:75], v[104:105], off offset:576
	s_waitcnt vmcnt(3)
	v_mfma_f32_32x32x16_bf16 v[16:31], v[88:91], v[84:87], v[16:31]
	global_load_dwordx4 v[84:87], v[106:107], off offset:576
	s_waitcnt vmcnt(3)
	v_mfma_f32_32x32x16_bf16 v[0:15], v[88:91], v[76:79], v[0:15]
	s_waitcnt vmcnt(1)
	v_mfma_f32_32x32x16_bf16 v[16:31], v[100:103], v[72:75], v[16:31]
	global_load_dwordx4 v[72:75], v[48:49], off offset:608
	s_waitcnt vmcnt(1)
	v_mfma_f32_32x32x16_bf16 v[0:15], v[100:103], v[84:87], v[0:15]
	global_load_dwordx4 v[76:79], v[104:105], off offset:608
	global_load_dwordx4 v[84:87], v[48:49], off offset:640
	global_load_dwordx4 v[88:91], v[104:105], off offset:640
	v_lshlrev_b64 v[48:49], 11, v[44:45]
	v_lshl_add_u64 v[46:47], v[46:47], 0, v[48:49]
	s_waitcnt vmcnt(2)
	v_mfma_f32_32x32x16_bf16 v[16:31], v[72:75], v[76:79], v[16:31]
	global_load_dwordx4 v[76:79], v[106:107], off offset:608
	global_load_dwordx4 v[96:99], v[106:107], off offset:640
	s_nop 0
	global_load_ushort v46, v[46:47], off
	v_lshlrev_b32_e32 v47, 16, v71
	s_waitcnt vmcnt(2)
	v_mfma_f32_32x32x16_bf16 v[0:15], v[72:75], v[76:79], v[0:15]
	global_load_dwordx4 v[72:75], v[106:107], off offset:672
	v_mfma_f32_32x32x16_bf16 v[16:31], v[84:87], v[88:91], v[16:31]
	s_waitcnt vmcnt(2)
	v_mfma_f32_32x32x16_bf16 v[0:15], v[84:87], v[96:99], v[0:15]
	v_mfma_f32_32x32x16_bf16 v[16:31], v[80:83], v[92:95], v[16:31]
	s_waitcnt vmcnt(0)
	v_mfma_f32_32x32x16_bf16 v[0:15], v[80:83], v[72:75], v[0:15]
	s_nop 9
	ds_write2st64_b32 v56, v16, v17 offset1:1
	ds_write2st64_b32 v56, v18, v19 offset0:2 offset1:3
	ds_write2st64_b32 v56, v20, v21 offset0:4 offset1:5
	ds_write2st64_b32 v56, v22, v23 offset0:6 offset1:7
	ds_write2st64_b32 v56, v24, v25 offset0:8 offset1:9
	ds_write2st64_b32 v56, v26, v27 offset0:10 offset1:11
	ds_write2st64_b32 v56, v28, v29 offset0:12 offset1:13
	ds_write2st64_b32 v56, v30, v31 offset0:14 offset1:15
	ds_write2st64_b32 v56, v0, v1 offset0:16 offset1:17
	ds_write2st64_b32 v56, v2, v3 offset0:18 offset1:19
	ds_write2st64_b32 v56, v4, v5 offset0:20 offset1:21
	ds_write2st64_b32 v56, v6, v7 offset0:22 offset1:23
	ds_write2st64_b32 v56, v8, v9 offset0:24 offset1:25
	ds_write2st64_b32 v56, v10, v11 offset0:26 offset1:27
	ds_write2st64_b32 v56, v12, v13 offset0:28 offset1:29
	ds_write2st64_b32 v56, v14, v15 offset0:30 offset1:31
	s_waitcnt lgkmcnt(0)
	s_barrier
	ds_read2st64_b32 v[0:1], v57 offset1:32
	ds_read2st64_b32 v[2:3], v57 offset0:64 offset1:96
	ds_read2st64_b32 v[4:5], v57 offset0:128 offset1:160
	v_lshlrev_b32_e32 v7, 16, v69
	v_lshlrev_b32_e32 v6, 16, v70
	s_waitcnt lgkmcnt(2)
	v_add_f32_e32 v0, 0, v0
	v_add_f32_e32 v0, v0, v1
	s_waitcnt lgkmcnt(1)
	v_add_f32_e32 v2, v0, v2
	ds_read2st64_b32 v[0:1], v57 offset0:192 offset1:224
	v_add_f32_e32 v2, v2, v3
	s_waitcnt lgkmcnt(1)
	v_add_f32_e32 v4, v2, v4
	ds_read2st64_b32 v[2:3], v58 offset1:32
	v_add_f32_e32 v4, v4, v5
	s_waitcnt lgkmcnt(1)
	v_add_f32_e32 v0, v4, v0
	ds_read2st64_b32 v[4:5], v58 offset0:64 offset1:96
	v_add_f32_e32 v9, v0, v1
	s_waitcnt lgkmcnt(1)
	v_add_f32_e32 v2, 0, v2
	ds_read2st64_b32 v[0:1], v58 offset0:128 offset1:160
	v_add_f32_e32 v2, v2, v3
	s_waitcnt lgkmcnt(1)
	v_add_f32_e32 v4, v2, v4
	ds_read2st64_b32 v[2:3], v58 offset0:192 offset1:224
	v_add_f32_e32 v4, v4, v5
	s_waitcnt lgkmcnt(1)
	v_add_f32_e32 v0, v4, v0
	ds_read2st64_b32 v[4:5], v59 offset1:32
	v_add_f32_e32 v0, v0, v1
	s_waitcnt lgkmcnt(1)
	v_add_f32_e32 v2, v0, v2
	ds_read2st64_b32 v[0:1], v59 offset0:64 offset1:96
	v_add_f32_e32 v10, v2, v3
	s_waitcnt lgkmcnt(1)
	v_add_f32_e32 v4, 0, v4
	ds_read2st64_b32 v[2:3], v59 offset0:128 offset1:160
	v_add_f32_e32 v4, v4, v5
	s_waitcnt lgkmcnt(1)
	v_add_f32_e32 v0, v4, v0
	ds_read2st64_b32 v[4:5], v59 offset0:192 offset1:224
	v_add_f32_e32 v0, v0, v1
	s_waitcnt lgkmcnt(1)
	v_add_f32_e32 v2, v0, v2
	ds_read2st64_b32 v[0:1], v60 offset1:32
	v_add_f32_e32 v2, v2, v3
	s_waitcnt lgkmcnt(1)
	v_add_f32_e32 v2, v2, v4
	v_add_f32_e32 v11, v2, v5
	ds_read2st64_b32 v[2:3], v60 offset0:64 offset1:96
	ds_read2st64_b32 v[4:5], v60 offset0:128 offset1:160
	s_waitcnt lgkmcnt(2)
	v_add_f32_e32 v0, 0, v0
	v_add_f32_e32 v12, v0, v1
	ds_read2st64_b32 v[0:1], v60 offset0:192 offset1:224
	s_waitcnt lgkmcnt(2)
	v_add_f32_e32 v2, v12, v2
	v_add_f32_e32 v2, v2, v3
	s_waitcnt lgkmcnt(1)
	v_add_f32_e32 v2, v2, v4
	v_add_f32_e32 v2, v2, v5
	s_waitcnt lgkmcnt(0)
	v_add_f32_e32 v0, v2, v0
	v_add_f32_e32 v2, v0, v1
	s_load_dwordx2 s[40:41], s[0:1], 0xf0
	s_load_dwordx4 s[44:47], s[0:1], 0xd8
	v_add_f32_e32 v12, v62, v9
	v_mul_f32_e32 v12, v61, v12
	v_fmac_f32_e32 v12, 0x3f9837f0, v7
	s_barrier
	v_lshlrev_b32_e32 v8, 16, v46
	v_add_f32_e32 v13, v65, v10
	v_mul_f32_e32 v13, v64, v13
	v_fmac_f32_e32 v13, 0x3f9837f0, v6
	v_add_f32_e32 v14, v63, v11
	v_mul_f32_e32 v14, v66, v14
	v_fmac_f32_e32 v14, 0x3f9837f0, v47
	v_add_f32_e32 v15, v68, v2
	v_mul_f32_e32 v15, v67, v15
	v_fmac_f32_e32 v15, 0x3f9837f0, v8
	s_lshr_b32 s48, s96, 4
	s_and_b32 s49, s96, 15
	s_lshl_b32 s51, s49, 3
	s_waitcnt lgkmcnt(0)
	global_load_dword v16, v32, s[44:45]
	global_load_dword v17, v32, s[46:47]
	s_lshl_b32 s50, s48, 12
	s_add_u32 s42, s40, 0xff00000
	s_addc_u32 s43, s41, 0
	s_add_u32 s42, s42, s50
	s_addc_u32 s43, s43, 0
	s_lshl_b32 s50, s48, 8
	s_add_u32 s40, s40, 0x27a4080
	s_addc_u32 s41, s41, 0
	s_add_u32 s40, s40, s50
	s_addc_u32 s41, s41, 0
	v_mov_b32_e32 v24, v12
	v_mov_b32_e32 v26, v13
	v_mov_b32_e32 v28, v14
	v_mov_b32_e32 v30, v15
	s_nop 1
	v_add_f32_dpp v24, v24, v24 quad_perm:[1,0,3,2] row_mask:0xf bank_mask:0xf
	v_add_f32_dpp v26, v26, v26 quad_perm:[1,0,3,2] row_mask:0xf bank_mask:0xf
	v_add_f32_dpp v28, v28, v28 quad_perm:[1,0,3,2] row_mask:0xf bank_mask:0xf
	v_add_f32_dpp v30, v30, v30 quad_perm:[1,0,3,2] row_mask:0xf bank_mask:0xf
	v_add_f32_dpp v24, v24, v24 quad_perm:[2,3,0,1] row_mask:0xf bank_mask:0xf
	v_add_f32_dpp v26, v26, v26 quad_perm:[2,3,0,1] row_mask:0xf bank_mask:0xf
	v_add_f32_dpp v28, v28, v28 quad_perm:[2,3,0,1] row_mask:0xf bank_mask:0xf
	v_add_f32_dpp v30, v30, v30 quad_perm:[2,3,0,1] row_mask:0xf bank_mask:0xf
	v_add_f32_dpp v24, v24, v24 row_half_mirror row_mask:0xf bank_mask:0xf
	v_add_f32_dpp v26, v26, v26 row_half_mirror row_mask:0xf bank_mask:0xf
	v_add_f32_dpp v28, v28, v28 row_half_mirror row_mask:0xf bank_mask:0xf
	v_add_f32_dpp v30, v30, v30 row_half_mirror row_mask:0xf bank_mask:0xf
	v_add_f32_dpp v24, v24, v24 row_mirror row_mask:0xf bank_mask:0xf
	v_add_f32_dpp v26, v26, v26 row_mirror row_mask:0xf bank_mask:0xf
	v_add_f32_dpp v28, v28, v28 row_mirror row_mask:0xf bank_mask:0xf
	v_add_f32_dpp v30, v30, v30 row_mirror row_mask:0xf bank_mask:0xf
	s_nop 1
	v_readlane_b32 s52, v24, 0
	v_readlane_b32 s53, v24, 16
	v_readlane_b32 s54, v24, 32
	v_readlane_b32 s55, v24, 48
	v_readlane_b32 s56, v26, 0
	v_readlane_b32 s57, v26, 16
	v_readlane_b32 s58, v26, 32
	v_readlane_b32 s59, v26, 48
	v_readlane_b32 s60, v28, 0
	v_readlane_b32 s61, v28, 16
	v_readlane_b32 s62, v28, 32
	v_readlane_b32 s63, v28, 48
	v_readlane_b32 s64, v30, 0
	v_readlane_b32 s65, v30, 16
	v_readlane_b32 s66, v30, 32
	v_readlane_b32 s67, v30, 48
	v_mov_b32_e32 v24, s52
	v_add_f32_e32 v24, s53, v24
	v_add_f32_e32 v24, s54, v24
	v_add_f32_e32 v24, s55, v24
	v_mov_b32_e32 v26, s56
	v_add_f32_e32 v26, s57, v26
	v_add_f32_e32 v26, s58, v26
	v_add_f32_e32 v26, s59, v26
	v_mov_b32_e32 v28, s60
	v_add_f32_e32 v28, s61, v28
	v_add_f32_e32 v28, s62, v28
	v_add_f32_e32 v28, s63, v28
	v_mov_b32_e32 v30, s64
	v_add_f32_e32 v30, s65, v30
	v_add_f32_e32 v30, s66, v30
	v_add_f32_e32 v30, s67, v30
	v_mul_f32_e32 v24, 0x3c800000, v24
	v_mul_f32_e32 v26, 0x3c800000, v26
	v_mul_f32_e32 v28, 0x3c800000, v28
	v_mul_f32_e32 v30, 0x3c800000, v30
	v_sub_f32_e32 v25, v12, v24
	v_sub_f32_e32 v27, v13, v26
	v_sub_f32_e32 v29, v14, v28
	v_sub_f32_e32 v31, v15, v30
	v_mul_f32_e32 v25, v25, v25
	v_mul_f32_e32 v27, v27, v27
	v_mul_f32_e32 v29, v29, v29
	v_mul_f32_e32 v31, v31, v31
	s_nop 1
	v_add_f32_dpp v25, v25, v25 quad_perm:[1,0,3,2] row_mask:0xf bank_mask:0xf
	v_add_f32_dpp v27, v27, v27 quad_perm:[1,0,3,2] row_mask:0xf bank_mask:0xf
	v_add_f32_dpp v29, v29, v29 quad_perm:[1,0,3,2] row_mask:0xf bank_mask:0xf
	v_add_f32_dpp v31, v31, v31 quad_perm:[1,0,3,2] row_mask:0xf bank_mask:0xf
	v_add_f32_dpp v25, v25, v25 quad_perm:[2,3,0,1] row_mask:0xf bank_mask:0xf
	v_add_f32_dpp v27, v27, v27 quad_perm:[2,3,0,1] row_mask:0xf bank_mask:0xf
	v_add_f32_dpp v29, v29, v29 quad_perm:[2,3,0,1] row_mask:0xf bank_mask:0xf
	v_add_f32_dpp v31, v31, v31 quad_perm:[2,3,0,1] row_mask:0xf bank_mask:0xf
	v_add_f32_dpp v25, v25, v25 row_half_mirror row_mask:0xf bank_mask:0xf
	v_add_f32_dpp v27, v27, v27 row_half_mirror row_mask:0xf bank_mask:0xf
	v_add_f32_dpp v29, v29, v29 row_half_mirror row_mask:0xf bank_mask:0xf
	v_add_f32_dpp v31, v31, v31 row_half_mirror row_mask:0xf bank_mask:0xf
	v_add_f32_dpp v25, v25, v25 row_mirror row_mask:0xf bank_mask:0xf
	v_add_f32_dpp v27, v27, v27 row_mirror row_mask:0xf bank_mask:0xf
	v_add_f32_dpp v29, v29, v29 row_mirror row_mask:0xf bank_mask:0xf
	v_add_f32_dpp v31, v31, v31 row_mirror row_mask:0xf bank_mask:0xf
	s_nop 1
	v_readlane_b32 s52, v25, 0
	v_readlane_b32 s53, v25, 16
	v_readlane_b32 s54, v25, 32
	v_readlane_b32 s55, v25, 48
	v_readlane_b32 s56, v27, 0
	v_readlane_b32 s57, v27, 16
	v_readlane_b32 s58, v27, 32
	v_readlane_b32 s59, v27, 48
	v_readlane_b32 s60, v29, 0
	v_readlane_b32 s61, v29, 16
	v_readlane_b32 s62, v29, 32
	v_readlane_b32 s63, v29, 48
	v_readlane_b32 s64, v31, 0
	v_readlane_b32 s65, v31, 16
	v_readlane_b32 s66, v31, 32
	v_readlane_b32 s67, v31, 48
	v_mov_b32_e32 v25, s52
	v_add_f32_e32 v25, s53, v25
	v_add_f32_e32 v25, s54, v25
	v_add_f32_e32 v25, s55, v25
	v_mov_b32_e32 v27, s56
	v_add_f32_e32 v27, s57, v27
	v_add_f32_e32 v27, s58, v27
	v_add_f32_e32 v27, s59, v27
	v_mov_b32_e32 v29, s60
	v_add_f32_e32 v29, s61, v29
	v_add_f32_e32 v29, s62, v29
	v_add_f32_e32 v29, s63, v29
	v_mov_b32_e32 v31, s64
	v_add_f32_e32 v31, s65, v31
	v_add_f32_e32 v31, s66, v31
	v_add_f32_e32 v31, s67, v31
	v_lshlrev_b32_e32 v20, 7, v51
	v_add_u32_e32 v20, s51, v20
	v_mov_b32_e32 v21, 0
	v_mov_b32_e32 v22, 1
	s_mov_b64 exec, 1
	global_store_dwordx2 v20, v[24:25], s[42:43] sc1
	global_store_dwordx2 v20, v[26:27], s[42:43] offset:1024 sc1
	global_store_dwordx2 v20, v[28:29], s[42:43] offset:2048 sc1
	global_store_dwordx2 v20, v[30:31], s[42:43] offset:3072 sc1
	s_waitcnt vmcnt(0)
	global_atomic_add v21, v22, s[40:41]
	s_mov_b64 exec, -1
	v_lshrrev_b32_e32 v20, 4, v50
	v_lshlrev_b32_e32 v20, 10, v20
	v_and_b32_e32 v23, 15, v50
	v_lshl_add_u32 v20, v23, 3, v20
	v_lshl_add_u32 v20, v51, 7, v20
	v_readfirstlane_b32 s58, v51
	s_movk_i32 s56, 0x2000
	s_cmp_lg_u32 s58, 0
	s_cbranch_scc1 .Lp12_go

.Lp12_go:
	s_barrier
	global_load_dwordx2 v[24:25], v20, s[42:43] sc1
	s_waitcnt vmcnt(0)
	v_mov_b32_e32 v26, v24
	s_nop 1
	v_add_f32_dpp v26, v26, v26 quad_perm:[1,0,3,2] row_mask:0xf bank_mask:0xf
	s_nop 1
	v_add_f32_dpp v26, v26, v26 quad_perm:[2,3,0,1] row_mask:0xf bank_mask:0xf
	s_nop 1
	v_add_f32_dpp v26, v26, v26 row_half_mirror row_mask:0xf bank_mask:0xf
	s_nop 1
	v_add_f32_dpp v26, v26, v26 row_mirror row_mask:0xf bank_mask:0xf
	v_mul_f32_e32 v26, 0x3d800000, v26
	v_sub_f32_e32 v27, v24, v26
	v_mul_f32_e32 v27, v27, v27
	v_fmac_f32_e32 v25, 0x42800000, v27
	s_nop 1
	v_add_f32_dpp v25, v25, v25 quad_perm:[1,0,3,2] row_mask:0xf bank_mask:0xf
	s_nop 1
	v_add_f32_dpp v25, v25, v25 quad_perm:[2,3,0,1] row_mask:0xf bank_mask:0xf
	s_nop 1
	v_add_f32_dpp v25, v25, v25 row_half_mirror row_mask:0xf bank_mask:0xf
	s_nop 1
	v_add_f32_dpp v25, v25, v25 row_mirror row_mask:0xf bank_mask:0xf
	v_mov_b32_e32 v28, 0x3727c5ac
	v_fmac_f32_e32 v28, 0x3a800000, v25
	v_rsq_f32_e32 v28, v28
	s_nop 1
	v_readlane_b32 s60, v26, 0
	v_readlane_b32 s61, v28, 0
	v_readlane_b32 s62, v26, 16
	v_readlane_b32 s63, v28, 16
	v_readlane_b32 s64, v26, 32
	v_readlane_b32 s65, v28, 32
	v_readlane_b32 s66, v26, 48
	v_readlane_b32 s67, v28, 48
	v_subrev_f32_e32 v12, s60, v12
	v_subrev_f32_e32 v13, s62, v13
	v_subrev_f32_e32 v14, s64, v14
	v_subrev_f32_e32 v15, s66, v15
	v_mul_f32_e32 v12, s61, v12
	v_mul_f32_e32 v13, s63, v13
	v_mul_f32_e32 v14, s65, v14
	v_mul_f32_e32 v15, s67, v15
	v_fma_f32 v12, v12, v16, v17
	v_fma_f32 v13, v13, v16, v17
	v_fma_f32 v14, v14, v16, v17
	v_fma_f32 v15, v15, v16, v17
	v_lshl_add_u32 v18, v38, 12, v32
	global_store_dword v18, v12, s[22:23]
	v_lshl_add_u32 v19, v40, 12, v32
	global_store_dword v19, v13, s[22:23]
	v_lshl_add_u32 v18, v42, 12, v32
	global_store_dword v18, v14, s[22:23]
	v_lshl_add_u32 v19, v44, 12, v32
	global_store_dword v19, v15, s[22:23]
	s_branch .LBB0_1349
